# out_proj epilogue: second-half residual loads issued early (group 0 into free registers, groups 1-2 as registers free up)
# baseline (speedup 1.0000x reference)
;     __device__ __forceinline__ void operator()(f32x4 (&acc)[2][2][4][2], const Unit& u, int wr, int wc, int fr, int fq) const {
;     ...
;         for (int ai = 0; ai < 2; ++ai) {
;             f32x4 xv[4][2][2];
; #pragma unroll
;             for (int m = 0; m < 4; ++m) {
;                 const int row = 256 * u.pm + 128 * ai + 64 * wr + 16 * m + fr;
; #pragma unroll
;                 for (int bj = 0; bj < 2; ++bj)
; #pragma unroll
;                     for (int n = 0; n < 2; ++n) xv[m][bj][n] = __builtin_nontemporal_load((const f32x4*)(x + (size_t)row * 1024 + 256 * u.pn + 64 * wc + 32 * bj + 8 * fq + 4 * n));
;             }
; #pragma unroll
;             for (int m = 0; m < 4; ++m) {
;                 const int row = 256 * u.pm + 128 * ai + 64 * wr + 16 * m + fr;
;                 float ss = 0.f;
; #pragma unroll
;                 for (int bj = 0; bj < 2; ++bj)
; #pragma unroll
;                     for (int n = 0; n < 2; ++n) {
;                         const f32x4 v = acc[ai][bj][m][n] + xv[m][bj][n];
;                         acc[ai][bj][m][n] = v;
;                         ss += (v[0] * v[0] + v[1] * v[1]) + (v[2] * v[2] + v[3] * v[3]);
;                     }
;                 ss += __shfl_xor(ss, 16); ss += __shfl_xor(ss, 32);
;                 if (fq == 0) SSQ[row * 16 + 4 * u.pn + wc] = ss;
;             }
.LBB0_491:
	v_lshl_add_u32 v184, s8, 8, v186
	s_lshl_b32 s34, s10, 8
	s_ashr_i32 s35, s34, 31
	v_ashrrev_i32_e32 v185, 31, v184
	v_lshl_add_u64 v[182:183], s[34:35], 2, v[176:177]
	v_lshlrev_b64 v[128:129], 12, v[184:185]
	v_lshl_add_u64 v[128:129], v[182:183], 0, v[128:129]
	global_load_dwordx4 v[206:209], v[128:129], off nt
	global_load_dwordx4 v[210:213], v[128:129], off offset:16 nt
	global_load_dwordx4 v[214:217], v[128:129], off offset:128 nt
	global_load_dwordx4 v[218:221], v[128:129], off offset:144 nt
	v_or_b32_e32 v128, 16, v184
	v_or_b32_e32 v130, 32, v184
	v_or_b32_e32 v132, 48, v184
	v_ashrrev_i32_e32 v129, 31, v128
	v_ashrrev_i32_e32 v131, 31, v130
	v_ashrrev_i32_e32 v133, 31, v132
	v_lshlrev_b64 v[128:129], 12, v[128:129]
	v_lshlrev_b64 v[130:131], 12, v[130:131]
	v_lshlrev_b64 v[132:133], 12, v[132:133]
	v_lshl_add_u64 v[128:129], v[182:183], 0, v[128:129]
	v_lshl_add_u64 v[130:131], v[182:183], 0, v[130:131]
	v_lshl_add_u64 v[132:133], v[182:183], 0, v[132:133]
	global_load_dwordx4 v[168:171], v[128:129], off offset:16 nt
	global_load_dwordx4 v[172:175], v[128:129], off nt
	global_load_dwordx4 v[160:163], v[128:129], off offset:144 nt
	global_load_dwordx4 v[164:167], v[128:129], off offset:128 nt
	global_load_dwordx4 v[152:155], v[130:131], off offset:16 nt
	global_load_dwordx4 v[156:159], v[130:131], off nt
	global_load_dwordx4 v[144:147], v[130:131], off offset:144 nt
	global_load_dwordx4 v[148:151], v[130:131], off offset:128 nt
	global_load_dwordx4 v[136:139], v[132:133], off offset:16 nt
	global_load_dwordx4 v[140:143], v[132:133], off nt
	s_nop 0
	global_load_dwordx4 v[128:131], v[132:133], off offset:144 nt
	s_nop 0
	global_load_dwordx4 v[132:135], v[132:133], off offset:128 nt
	v_add_u32_e32 v240, 0x80, v184
	v_ashrrev_i32_e32 v241, 31, v240
	v_lshlrev_b64 v[240:241], 12, v[240:241]
	v_lshl_add_u64 v[240:241], v[182:183], 0, v[240:241]
	global_load_dwordx4 v[224:227], v[240:241], off nt
	global_load_dwordx4 v[228:231], v[240:241], off offset:16 nt
	global_load_dwordx4 v[232:235], v[240:241], off offset:128 nt
	global_load_dwordx4 v[236:239], v[240:241], off offset:144 nt
	v_xor_b32_e32 v185, 16, v192
	v_cmp_lt_i32_e32 vcc, v185, v202
	s_waitcnt vmcnt(4)
	v_pk_add_f32 v[126:127], v[126:127], v[208:209]
	v_pk_add_f32 v[124:125], v[124:125], v[206:207]
	v_pk_add_f32 v[122:123], v[122:123], v[212:213]
	v_pk_add_f32 v[120:121], v[120:121], v[210:211]
	v_pk_add_f32 v[118:119], v[118:119], v[216:217]
	v_pk_add_f32 v[116:117], v[116:117], v[214:215]
	v_mul_f32_e32 v206, v125, v125
	v_mul_f32_e32 v207, v127, v127
	v_mul_f32_e32 v208, v121, v121
	v_mul_f32_e32 v209, v123, v123
	v_pk_add_f32 v[114:115], v[114:115], v[220:221]
	v_pk_add_f32 v[112:113], v[112:113], v[218:219]
	v_mul_f32_e32 v210, v117, v117
	v_mul_f32_e32 v211, v119, v119
	v_fmac_f32_e32 v206, v124, v124
	v_fmac_f32_e32 v207, v126, v126
	v_fmac_f32_e32 v208, v120, v120
	v_fmac_f32_e32 v209, v122, v122
	v_mul_f32_e32 v212, v113, v113
	v_mul_f32_e32 v213, v115, v115
	v_fmac_f32_e32 v210, v116, v116
	v_fmac_f32_e32 v211, v118, v118
	v_add_f32_e32 v206, v206, v207
	v_add_f32_e32 v207, v208, v209
	v_fmac_f32_e32 v212, v112, v112
	v_fmac_f32_e32 v213, v114, v114
	v_add_f32_e32 v208, v210, v211
	v_add_f32_e32 v206, v206, v207
	v_cndmask_b32_e32 v185, v192, v185, vcc
	v_add_f32_e32 v206, v206, v208
	v_add_f32_e32 v207, v212, v213
	v_lshlrev_b32_e32 v185, 2, v185
	v_add_f32_e32 v207, v206, v207
	ds_bpermute_b32 v208, v185, v207
	v_cmp_lt_i32_e32 vcc, v193, v202
	s_waitcnt lgkmcnt(0)
	v_add_f32_e32 v207, v207, v208
	v_cndmask_b32_e32 v206, v192, v193, vcc
	v_lshlrev_b32_e32 v206, 2, v206
	ds_bpermute_b32 v208, v206, v207
	s_and_saveexec_b64 s[34:35], s[4:5]
	s_cbranch_execz .LBB0_493
	s_lshl_b32 s19, s8, 12
	s_lshl_b32 s21, s10, 2
	s_add_i32 s19, s19, s21
	s_waitcnt lgkmcnt(0)
	v_add_f32_e32 v207, v207, v208
	v_add_u32_e32 v208, s19, v188
	v_ashrrev_i32_e32 v209, 31, v208
	v_lshl_add_u64 v[208:209], v[208:209], 2, s[6:7]
	global_store_dword v[208:209], v207, off

;     __device__ __forceinline__ void operator()(f32x4 (&acc)[2][2][4][2], const Unit& u, int wr, int wc, int fr, int fq) const {
;     ...
;         for (int ai = 0; ai < 2; ++ai) {
;             f32x4 xv[4][2][2];
; #pragma unroll
;             for (int m = 0; m < 4; ++m) {
;                 const int row = 256 * u.pm + 128 * ai + 64 * wr + 16 * m + fr;
; #pragma unroll
;                 for (int bj = 0; bj < 2; ++bj)
; #pragma unroll
;                     for (int n = 0; n < 2; ++n) xv[m][bj][n] = __builtin_nontemporal_load((const f32x4*)(x + (size_t)row * 1024 + 256 * u.pn + 64 * wc + 32 * bj + 8 * fq + 4 * n));
;             }
; #pragma unroll
;             for (int m = 0; m < 4; ++m) {
;                 const int row = 256 * u.pm + 128 * ai + 64 * wr + 16 * m + fr;
;                 float ss = 0.f;
; #pragma unroll
;                 for (int bj = 0; bj < 2; ++bj)
; #pragma unroll
;                     for (int n = 0; n < 2; ++n) {
;                         const f32x4 v = acc[ai][bj][m][n] + xv[m][bj][n];
;                         acc[ai][bj][m][n] = v;
;                         ss += (v[0] * v[0] + v[1] * v[1]) + (v[2] * v[2] + v[3] * v[3]);
;                     }
;                 ss += __shfl_xor(ss, 16); ss += __shfl_xor(ss, 32);
;                 if (fq == 0) SSQ[row * 16 + 4 * u.pn + wc] = ss;
;             }
.LBB0_495:
	s_or_b64 exec, exec, s[34:35]
	v_add_u32_e32 v242, 0x90, v184
	v_ashrrev_i32_e32 v243, 31, v242
	v_lshlrev_b64 v[242:243], 12, v[242:243]
	v_lshl_add_u64 v[242:243], v[182:183], 0, v[242:243]
	global_load_dwordx4 v[168:171], v[242:243], off offset:16 nt
	global_load_dwordx4 v[172:175], v[242:243], off nt
	global_load_dwordx4 v[160:163], v[242:243], off offset:144 nt
	global_load_dwordx4 v[164:167], v[242:243], off offset:128 nt
	v_pk_add_f32 v[94:95], v[94:95], v[158:159]
	v_pk_add_f32 v[92:93], v[92:93], v[156:157]
	v_pk_add_f32 v[90:91], v[90:91], v[154:155]
	v_pk_add_f32 v[88:89], v[88:89], v[152:153]
	v_mul_f32_e32 v156, v93, v93
	v_mul_f32_e32 v157, v95, v95
	v_mul_f32_e32 v152, v89, v89
	v_mul_f32_e32 v153, v91, v91
	v_pk_add_f32 v[86:87], v[86:87], v[150:151]
	v_pk_add_f32 v[84:85], v[84:85], v[148:149]
	v_fmac_f32_e32 v156, v92, v92
	v_fmac_f32_e32 v157, v94, v94
	v_fmac_f32_e32 v152, v88, v88
	v_fmac_f32_e32 v153, v90, v90
	v_mul_f32_e32 v148, v85, v85
	v_mul_f32_e32 v149, v87, v87
	v_pk_add_f32 v[82:83], v[82:83], v[146:147]
	v_pk_add_f32 v[80:81], v[80:81], v[144:145]
	v_add_f32_e32 v156, v156, v157
	v_add_f32_e32 v152, v152, v153
	v_fmac_f32_e32 v148, v84, v84
	v_fmac_f32_e32 v149, v86, v86
	v_mul_f32_e32 v144, v81, v81
	v_mul_f32_e32 v145, v83, v83
	v_add_f32_e32 v152, v156, v152
	v_add_f32_e32 v148, v148, v149
	v_fmac_f32_e32 v144, v80, v80
	v_fmac_f32_e32 v145, v82, v82
	v_add_f32_e32 v148, v152, v148
	v_add_f32_e32 v144, v144, v145
	v_add_f32_e32 v144, v148, v144
	ds_bpermute_b32 v145, v185, v144
	s_waitcnt lgkmcnt(0)
	v_add_f32_e32 v144, v144, v145
	ds_bpermute_b32 v145, v206, v144
	s_and_saveexec_b64 s[34:35], s[4:5]
	s_cbranch_execz .LBB0_497
	s_lshl_b32 s19, s8, 12
	s_lshl_b32 s21, s10, 2
	s_add_i32 s19, s19, s21
	s_waitcnt lgkmcnt(0)
	v_add_f32_e32 v146, v144, v145
	v_add_u32_e32 v144, s19, v190
	v_ashrrev_i32_e32 v145, 31, v144
	v_lshl_add_u64 v[144:145], v[144:145], 2, s[6:7]
	global_store_dword v[144:145], v146, off
.LBB0_497:
	s_or_b64 exec, exec, s[34:35]
	v_add_u32_e32 v244, 0xa0, v184
	v_ashrrev_i32_e32 v245, 31, v244
	v_lshlrev_b64 v[244:245], 12, v[244:245]
	v_lshl_add_u64 v[244:245], v[182:183], 0, v[244:245]
	global_load_dwordx4 v[152:155], v[244:245], off offset:16 nt
	global_load_dwordx4 v[156:159], v[244:245], off nt
	global_load_dwordx4 v[144:147], v[244:245], off offset:144 nt
	global_load_dwordx4 v[148:151], v[244:245], off offset:128 nt
	v_pk_add_f32 v[78:79], v[78:79], v[142:143]
	v_pk_add_f32 v[76:77], v[76:77], v[140:141]
	v_pk_add_f32 v[74:75], v[74:75], v[138:139]
	v_pk_add_f32 v[72:73], v[72:73], v[136:137]
	v_mul_f32_e32 v140, v77, v77
	v_mul_f32_e32 v141, v79, v79
	v_mul_f32_e32 v136, v73, v73
	v_mul_f32_e32 v137, v75, v75
	v_pk_add_f32 v[70:71], v[70:71], v[134:135]
	v_pk_add_f32 v[68:69], v[68:69], v[132:133]
	v_fmac_f32_e32 v140, v76, v76
	v_fmac_f32_e32 v141, v78, v78
	v_fmac_f32_e32 v136, v72, v72
	v_fmac_f32_e32 v137, v74, v74
	v_mul_f32_e32 v132, v69, v69
	v_mul_f32_e32 v133, v71, v71
	v_pk_add_f32 v[66:67], v[66:67], v[130:131]
	v_pk_add_f32 v[64:65], v[64:65], v[128:129]
	v_add_f32_e32 v140, v140, v141
	v_add_f32_e32 v136, v136, v137
	v_fmac_f32_e32 v132, v68, v68
	v_fmac_f32_e32 v133, v70, v70
	v_mul_f32_e32 v128, v65, v65
	v_mul_f32_e32 v129, v67, v67
	v_add_f32_e32 v136, v140, v136
	v_add_f32_e32 v132, v132, v133
	v_fmac_f32_e32 v128, v64, v64
	v_fmac_f32_e32 v129, v66, v66
	v_add_f32_e32 v132, v136, v132
	v_add_f32_e32 v128, v128, v129
	v_add_f32_e32 v128, v132, v128
	ds_bpermute_b32 v129, v185, v128
	s_waitcnt lgkmcnt(0)
	v_add_f32_e32 v128, v128, v129
	ds_bpermute_b32 v129, v206, v128
	s_and_saveexec_b64 s[34:35], s[4:5]
	s_cbranch_execz .LBB0_499
	s_lshl_b32 s19, s8, 12
	s_lshl_b32 s21, s10, 2
	s_add_i32 s19, s19, s21
	s_waitcnt lgkmcnt(0)
	v_add_f32_e32 v130, v128, v129
	v_add_u32_e32 v128, s19, v191
	v_ashrrev_i32_e32 v129, 31, v128
	v_lshl_add_u64 v[128:129], v[128:129], 2, s[6:7]
	global_store_dword v[128:129], v130, off
.LBB0_499:
	s_or_b64 exec, exec, s[34:35]
	v_add_u32_e32 v128, 0x80, v184
	s_waitcnt lgkmcnt(0)
	v_ashrrev_i32_e32 v129, 31, v128
	v_lshlrev_b64 v[128:129], 12, v[128:129]
	v_lshl_add_u64 v[128:129], v[182:183], 0, v[128:129]
	v_add_u32_e32 v128, 0x90, v184
	v_add_u32_e32 v130, 0xa0, v184
	v_add_u32_e32 v132, 0xb0, v184
	v_ashrrev_i32_e32 v129, 31, v128
	v_ashrrev_i32_e32 v131, 31, v130
	v_ashrrev_i32_e32 v133, 31, v132
	v_lshlrev_b64 v[128:129], 12, v[128:129]
	v_lshlrev_b64 v[130:131], 12, v[130:131]
	v_lshlrev_b64 v[132:133], 12, v[132:133]
	v_lshl_add_u64 v[128:129], v[182:183], 0, v[128:129]
	v_lshl_add_u64 v[130:131], v[182:183], 0, v[130:131]
	v_lshl_add_u64 v[132:133], v[182:183], 0, v[132:133]
	global_load_dwordx4 v[136:139], v[132:133], off offset:16 nt
	global_load_dwordx4 v[140:143], v[132:133], off nt
	s_nop 0
	global_load_dwordx4 v[128:131], v[132:133], off offset:144 nt
	s_nop 0
	global_load_dwordx4 v[132:135], v[132:133], off offset:128 nt
	s_waitcnt vmcnt(15)
	v_pk_add_f32 v[62:63], v[62:63], v[226:227]
	v_pk_add_f32 v[60:61], v[60:61], v[224:225]
	s_waitcnt vmcnt(14)
	v_pk_add_f32 v[58:59], v[58:59], v[230:231]
	v_pk_add_f32 v[56:57], v[56:57], v[228:229]
	s_waitcnt vmcnt(13)
	v_pk_add_f32 v[54:55], v[54:55], v[234:235]
	v_pk_add_f32 v[52:53], v[52:53], v[232:233]
	v_mul_f32_e32 v182, v61, v61
	v_mul_f32_e32 v183, v63, v63
	v_mul_f32_e32 v184, v57, v57
	v_mul_f32_e32 v207, v59, v59
	s_waitcnt vmcnt(12)
	v_pk_add_f32 v[50:51], v[50:51], v[238:239]
	v_pk_add_f32 v[48:49], v[48:49], v[236:237]
	v_mul_f32_e32 v208, v53, v53
	v_mul_f32_e32 v209, v55, v55
	v_fmac_f32_e32 v182, v60, v60
	v_fmac_f32_e32 v183, v62, v62
	v_fmac_f32_e32 v184, v56, v56
	v_fmac_f32_e32 v207, v58, v58
	v_mul_f32_e32 v210, v49, v49
	v_mul_f32_e32 v211, v51, v51
	v_fmac_f32_e32 v208, v52, v52
	v_fmac_f32_e32 v209, v54, v54
	v_add_f32_e32 v182, v182, v183
	v_add_f32_e32 v183, v184, v207
	v_fmac_f32_e32 v210, v48, v48
	v_fmac_f32_e32 v211, v50, v50
	v_add_f32_e32 v184, v208, v209
	v_add_f32_e32 v182, v182, v183
	v_add_f32_e32 v182, v182, v184
	v_add_f32_e32 v183, v210, v211
	v_add_f32_e32 v182, v182, v183
	ds_bpermute_b32 v183, v185, v182
	s_waitcnt lgkmcnt(0)
	v_add_f32_e32 v182, v182, v183
	ds_bpermute_b32 v183, v206, v182
	s_and_saveexec_b64 s[34:35], s[4:5]
	s_cbranch_execz .LBB0_501
	s_lshl_b32 s19, s8, 12
	s_lshl_b32 s21, s10, 2
	s_add_i32 s19, s19, s21
	s_waitcnt lgkmcnt(0)
	v_add_f32_e32 v184, v182, v183
	v_add_u32_e32 v182, s19, v200
	v_ashrrev_i32_e32 v183, 31, v182
	v_lshl_add_u64 v[182:183], v[182:183], 2, s[6:7]
	global_store_dword v[182:183], v184, off
